# v024 + SSD scan unit: the 16 per-row decay-read/exp/store ladders of both y-store blocks batched (4 ds_read_b128 + one wait, immediate store offsets, forward/backward copies)
# baseline (speedup 1.0000x reference)
.LBB0_821:
	s_waitcnt vmcnt(0)
	s_and_b64 s[10:11], s[46:47], s[66:67]
	s_or_b64 s[10:11], s[56:57], s[10:11]
	s_lshl_b32 s8, s75, 7
	s_and_b64 vcc, exec, s[10:11]
	s_cbranch_vccnz .LBB0_823
	v_add_u32_e32 v4, s22, v209
	s_or_b32 s9, s8, 0x7f
	v_lshlrev_b32_e32 v0, 1, v200
	v_lshl_add_u64 v[2:3], s[70:71], 0, v[0:1]
	v_lshl_add_u32 v0, v4, 2, s74
	ds_read_b128 v[64:67], v0
	ds_read_b128 v[68:71], v0 offset:32
	ds_read_b128 v[72:75], v0 offset:64
	ds_read_b128 v[76:79], v0 offset:96
	v_sub_u32_e32 v0, s9, v4
	v_add_u32_e32 v5, s8, v4
	v_cndmask_b32_e64 v6, v0, v5, s[4:5]
	v_ashrrev_i32_e32 v7, 31, v6
	v_lshlrev_b64 v[6:7], 9, v[6:7]
	v_lshl_add_u64 v[6:7], v[2:3], 0, v[6:7]
	s_and_b64 vcc, exec, s[4:5]
	s_cbranch_vccz .Lssd_y1_bwd
	v_add_co_u32_e32 v80, vcc, 0x1000, v6
	v_addc_co_u32_e32 v81, vcc, 0, v7, vcc
	v_add_co_u32_e32 v82, vcc, 0x2000, v6
	v_addc_co_u32_e32 v83, vcc, 0, v7, vcc
	v_add_co_u32_e32 v84, vcc, 0x3000, v6
	v_addc_co_u32_e32 v85, vcc, 0, v7, vcc
	s_waitcnt lgkmcnt(0)
	v_mul_f32_e32 v64, 0x3fb8aa3b, v64
	v_mul_f32_e32 v65, 0x3fb8aa3b, v65
	v_mul_f32_e32 v66, 0x3fb8aa3b, v66
	v_mul_f32_e32 v67, 0x3fb8aa3b, v67
	v_exp_f32_e32 v64, v64
	v_exp_f32_e32 v65, v65
	v_exp_f32_e32 v66, v66
	v_exp_f32_e32 v67, v67
	v_fma_f32 v64, v32, v64, v48
	v_fma_f32 v65, v33, v65, v49
	v_fma_f32 v66, v34, v66, v50
	v_fma_f32 v67, v35, v67, v51
	v_cvt_pk_bf16_f32 v64, v64, v1
	v_cvt_pk_bf16_f32 v65, v65, v1
	v_cvt_pk_bf16_f32 v66, v66, v1
	v_cvt_pk_bf16_f32 v67, v67, v1
	global_store_short v[6:7], v64, off
	global_store_short v[6:7], v65, off offset:512
	global_store_short v[6:7], v66, off offset:1024
	global_store_short v[6:7], v67, off offset:1536
	v_mul_f32_e32 v68, 0x3fb8aa3b, v68
	v_mul_f32_e32 v69, 0x3fb8aa3b, v69
	v_mul_f32_e32 v70, 0x3fb8aa3b, v70
	v_mul_f32_e32 v71, 0x3fb8aa3b, v71
	v_exp_f32_e32 v68, v68
	v_exp_f32_e32 v69, v69
	v_exp_f32_e32 v70, v70
	v_exp_f32_e32 v71, v71
	v_fma_f32 v68, v36, v68, v52
	v_fma_f32 v69, v37, v69, v53
	v_fma_f32 v70, v38, v70, v54
	v_fma_f32 v71, v39, v71, v55
	v_cvt_pk_bf16_f32 v68, v68, v1
	v_cvt_pk_bf16_f32 v69, v69, v1
	v_cvt_pk_bf16_f32 v70, v70, v1
	v_cvt_pk_bf16_f32 v71, v71, v1
	global_store_short v[80:81], v68, off
	global_store_short v[80:81], v69, off offset:512
	global_store_short v[80:81], v70, off offset:1024
	global_store_short v[80:81], v71, off offset:1536
	v_mul_f32_e32 v72, 0x3fb8aa3b, v72
	v_mul_f32_e32 v73, 0x3fb8aa3b, v73
	v_mul_f32_e32 v74, 0x3fb8aa3b, v74
	v_mul_f32_e32 v75, 0x3fb8aa3b, v75
	v_exp_f32_e32 v72, v72
	v_exp_f32_e32 v73, v73
	v_exp_f32_e32 v74, v74
	v_exp_f32_e32 v75, v75
	v_fma_f32 v72, v40, v72, v56
	v_fma_f32 v73, v41, v73, v57
	v_fma_f32 v74, v42, v74, v58
	v_fma_f32 v75, v43, v75, v59
	v_cvt_pk_bf16_f32 v72, v72, v1
	v_cvt_pk_bf16_f32 v73, v73, v1
	v_cvt_pk_bf16_f32 v74, v74, v1
	v_cvt_pk_bf16_f32 v75, v75, v1
	global_store_short v[82:83], v72, off
	global_store_short v[82:83], v73, off offset:512
	global_store_short v[82:83], v74, off offset:1024
	global_store_short v[82:83], v75, off offset:1536
	v_mul_f32_e32 v76, 0x3fb8aa3b, v76
	v_mul_f32_e32 v77, 0x3fb8aa3b, v77
	v_mul_f32_e32 v78, 0x3fb8aa3b, v78
	v_mul_f32_e32 v79, 0x3fb8aa3b, v79
	v_exp_f32_e32 v76, v76
	v_exp_f32_e32 v77, v77
	v_exp_f32_e32 v78, v78
	v_exp_f32_e32 v79, v79
	v_fma_f32 v76, v44, v76, v60
	v_fma_f32 v77, v45, v77, v61
	v_fma_f32 v78, v46, v78, v62
	v_fma_f32 v79, v47, v79, v63
	v_cvt_pk_bf16_f32 v76, v76, v1
	v_cvt_pk_bf16_f32 v77, v77, v1
	v_cvt_pk_bf16_f32 v78, v78, v1
	v_cvt_pk_bf16_f32 v79, v79, v1
	global_store_short v[84:85], v76, off
	global_store_short v[84:85], v77, off offset:512
	global_store_short v[84:85], v78, off offset:1024
	global_store_short v[84:85], v79, off offset:1536
	s_branch .Lssd_y1_done
.Lssd_y1_bwd:
	v_add_co_u32_e32 v80, vcc, 0xfffff000, v6
	v_addc_co_u32_e32 v81, vcc, -1, v7, vcc
	v_add_co_u32_e32 v82, vcc, 0xffffe000, v6
	v_addc_co_u32_e32 v83, vcc, -1, v7, vcc
	v_add_co_u32_e32 v84, vcc, 0xffffd000, v6
	v_addc_co_u32_e32 v85, vcc, -1, v7, vcc
	s_waitcnt lgkmcnt(0)
	v_mul_f32_e32 v64, 0x3fb8aa3b, v64
	v_mul_f32_e32 v65, 0x3fb8aa3b, v65
	v_mul_f32_e32 v66, 0x3fb8aa3b, v66
	v_mul_f32_e32 v67, 0x3fb8aa3b, v67
	v_exp_f32_e32 v64, v64
	v_exp_f32_e32 v65, v65
	v_exp_f32_e32 v66, v66
	v_exp_f32_e32 v67, v67
	v_fma_f32 v64, v32, v64, v48
	v_fma_f32 v65, v33, v65, v49
	v_fma_f32 v66, v34, v66, v50
	v_fma_f32 v67, v35, v67, v51
	v_cvt_pk_bf16_f32 v64, v64, v1
	v_cvt_pk_bf16_f32 v65, v65, v1
	v_cvt_pk_bf16_f32 v66, v66, v1
	v_cvt_pk_bf16_f32 v67, v67, v1
	global_store_short v[6:7], v64, off
	global_store_short v[6:7], v65, off offset:-512
	global_store_short v[6:7], v66, off offset:-1024
	global_store_short v[6:7], v67, off offset:-1536
	v_mul_f32_e32 v68, 0x3fb8aa3b, v68
	v_mul_f32_e32 v69, 0x3fb8aa3b, v69
	v_mul_f32_e32 v70, 0x3fb8aa3b, v70
	v_mul_f32_e32 v71, 0x3fb8aa3b, v71
	v_exp_f32_e32 v68, v68
	v_exp_f32_e32 v69, v69
	v_exp_f32_e32 v70, v70
	v_exp_f32_e32 v71, v71
	v_fma_f32 v68, v36, v68, v52
	v_fma_f32 v69, v37, v69, v53
	v_fma_f32 v70, v38, v70, v54
	v_fma_f32 v71, v39, v71, v55
	v_cvt_pk_bf16_f32 v68, v68, v1
	v_cvt_pk_bf16_f32 v69, v69, v1
	v_cvt_pk_bf16_f32 v70, v70, v1
	v_cvt_pk_bf16_f32 v71, v71, v1
	global_store_short v[80:81], v68, off
	global_store_short v[80:81], v69, off offset:-512
	global_store_short v[80:81], v70, off offset:-1024
	global_store_short v[80:81], v71, off offset:-1536
	v_mul_f32_e32 v72, 0x3fb8aa3b, v72
	v_mul_f32_e32 v73, 0x3fb8aa3b, v73
	v_mul_f32_e32 v74, 0x3fb8aa3b, v74
	v_mul_f32_e32 v75, 0x3fb8aa3b, v75
	v_exp_f32_e32 v72, v72
	v_exp_f32_e32 v73, v73
	v_exp_f32_e32 v74, v74
	v_exp_f32_e32 v75, v75
	v_fma_f32 v72, v40, v72, v56
	v_fma_f32 v73, v41, v73, v57
	v_fma_f32 v74, v42, v74, v58
	v_fma_f32 v75, v43, v75, v59
	v_cvt_pk_bf16_f32 v72, v72, v1
	v_cvt_pk_bf16_f32 v73, v73, v1
	v_cvt_pk_bf16_f32 v74, v74, v1
	v_cvt_pk_bf16_f32 v75, v75, v1
	global_store_short v[82:83], v72, off
	global_store_short v[82:83], v73, off offset:-512
	global_store_short v[82:83], v74, off offset:-1024
	global_store_short v[82:83], v75, off offset:-1536
	v_mul_f32_e32 v76, 0x3fb8aa3b, v76
	v_mul_f32_e32 v77, 0x3fb8aa3b, v77
	v_mul_f32_e32 v78, 0x3fb8aa3b, v78
	v_mul_f32_e32 v79, 0x3fb8aa3b, v79
	v_exp_f32_e32 v76, v76
	v_exp_f32_e32 v77, v77
	v_exp_f32_e32 v78, v78
	v_exp_f32_e32 v79, v79
	v_fma_f32 v76, v44, v76, v60
	v_fma_f32 v77, v45, v77, v61
	v_fma_f32 v78, v46, v78, v62
	v_fma_f32 v79, v47, v79, v63
	v_cvt_pk_bf16_f32 v76, v76, v1
	v_cvt_pk_bf16_f32 v77, v77, v1
	v_cvt_pk_bf16_f32 v78, v78, v1
	v_cvt_pk_bf16_f32 v79, v79, v1
	global_store_short v[84:85], v76, off
	global_store_short v[84:85], v77, off offset:-512
	global_store_short v[84:85], v78, off offset:-1024
	global_store_short v[84:85], v79, off offset:-1536
.Lssd_y1_done:
.LBB0_823:
	s_and_b64 vcc, exec, s[6:7]
	s_cbranch_vccnz .LBB0_825
	v_add_u32_e32 v0, s58, v212
	ds_read_b64_tr_b16 v[2:3], v0 offset:0
	ds_read_b64_tr_b16 v[4:5], v0 offset:0x400
	ds_read_b64_tr_b16 v[6:7], v0 offset:0x800
	ds_read_b64_tr_b16 v[8:9], v0 offset:0xc00
	v_add_u32_e32 v88, s59, v211
	ds_read_b64_tr_b16 v[64:65], v88 offset:0
	ds_read_b64_tr_b16 v[66:67], v88 offset:0x400
	ds_read_b64_tr_b16 v[80:81], v88 offset:0x800
	ds_read_b64_tr_b16 v[82:83], v88 offset:0xc00
	s_waitcnt lgkmcnt(0)
	s_nop 0
	v_mfma_f32_32x32x16_bf16 v[64:79], v[2:5], v[64:67], 0
	v_add_u32_e32 v89, 0x1000, v88
	v_mfma_f32_32x32x16_bf16 v[64:79], v[6:9], v[80:83], v[64:79]
	v_add_u32_e32 v80, 0x1000, v0
	ds_read_b64_tr_b16 v[2:3], v80 offset:0
	ds_read_b64_tr_b16 v[4:5], v80 offset:0x400
	ds_read_b64_tr_b16 v[6:7], v80 offset:0x800
	ds_read_b64_tr_b16 v[8:9], v80 offset:0xc00
	ds_read_b64_tr_b16 v[80:81], v89 offset:0
	ds_read_b64_tr_b16 v[82:83], v89 offset:0x400
	ds_read_b64_tr_b16 v[84:85], v89 offset:0x800
	ds_read_b64_tr_b16 v[86:87], v89 offset:0xc00
	s_waitcnt lgkmcnt(0)
	s_nop 1
	v_mfma_f32_32x32x16_bf16 v[64:79], v[2:5], v[80:83], v[64:79]
	v_add_u32_e32 v80, 0x2000, v0
	ds_read_b64_tr_b16 v[2:3], v80 offset:0
	ds_read_b64_tr_b16 v[4:5], v80 offset:0x400
	v_add_u32_e32 v89, 0x2000, v88
	v_mfma_f32_32x32x16_bf16 v[64:79], v[6:9], v[84:87], v[64:79]
	ds_read_b64_tr_b16 v[6:7], v80 offset:0x800
	ds_read_b64_tr_b16 v[8:9], v80 offset:0xc00
	ds_read_b64_tr_b16 v[80:81], v89 offset:0
	ds_read_b64_tr_b16 v[82:83], v89 offset:0x400
	ds_read_b64_tr_b16 v[84:85], v89 offset:0x800
	ds_read_b64_tr_b16 v[86:87], v89 offset:0xc00
	s_waitcnt lgkmcnt(0)
	s_nop 0
	v_mfma_f32_32x32x16_bf16 v[64:79], v[2:5], v[80:83], v[64:79]
	v_add_u32_e32 v0, 0x3000, v0
	ds_read_b64_tr_b16 v[2:3], v0 offset:0
	ds_read_b64_tr_b16 v[4:5], v0 offset:0x400
	v_mfma_f32_32x32x16_bf16 v[64:79], v[6:9], v[84:87], v[64:79]
	ds_read_b64_tr_b16 v[6:7], v0 offset:0x800
	ds_read_b64_tr_b16 v[8:9], v0 offset:0xc00
	v_add_u32_e32 v0, 0x3000, v88
	ds_read_b64_tr_b16 v[80:81], v0 offset:0
	ds_read_b64_tr_b16 v[82:83], v0 offset:0x400
	ds_read_b64_tr_b16 v[84:85], v0 offset:0x800
	ds_read_b64_tr_b16 v[86:87], v0 offset:0xc00
	s_waitcnt lgkmcnt(0)
	s_nop 0
	v_mfma_f32_32x32x16_bf16 v[64:79], v[2:5], v[80:83], v[64:79]
	v_mul_f32_e32 v0, 0x3fb8aa3b, v210
	v_exp_f32_e32 v0, v0
	v_mfma_f32_32x32x16_bf16 v[64:79], v[6:9], v[84:87], v[64:79]
	s_nop 11
	v_pk_fma_f32 v[30:31], v[30:31], v[0:1], v[78:79] op_sel_hi:[1,0,1]
	v_pk_fma_f32 v[28:29], v[28:29], v[0:1], v[76:77] op_sel_hi:[1,0,1]
	v_pk_fma_f32 v[26:27], v[26:27], v[0:1], v[74:75] op_sel_hi:[1,0,1]
	v_pk_fma_f32 v[24:25], v[24:25], v[0:1], v[72:73] op_sel_hi:[1,0,1]
	v_pk_fma_f32 v[22:23], v[22:23], v[0:1], v[70:71] op_sel_hi:[1,0,1]
	v_pk_fma_f32 v[20:21], v[20:21], v[0:1], v[68:69] op_sel_hi:[1,0,1]
	v_pk_fma_f32 v[18:19], v[18:19], v[0:1], v[66:67] op_sel_hi:[1,0,1]
	v_pk_fma_f32 v[16:17], v[16:17], v[0:1], v[64:65] op_sel_hi:[1,0,1]
.LBB0_825:
	s_waitcnt lgkmcnt(0)
	s_barrier
	s_mov_b64 s[6:7], -1
	s_and_b64 vcc, exec, s[54:55]
	s_cbranch_vccz .LBB0_830
	s_cmp_lt_u32 s25, 2
	v_readlane_b32 s10, v254, 59
	s_cselect_b64 s[6:7], -1, 0
	v_readlane_b32 s11, v254, 60
	s_and_b64 s[6:7], s[10:11], s[6:7]
	s_and_b64 vcc, exec, s[6:7]
	s_cbranch_vccnz .LBB0_828
	v_add_u32_e32 v6, s22, v209
	v_lshl_add_u32 v7, v192, 2, s89
	v_lshl_add_u32 v8, v6, 2, s74
	ds_read_b128 v[64:67], v8
	ds_read_b128 v[68:71], v8 offset:32
	ds_read_b128 v[72:75], v8 offset:64
	ds_read_b128 v[76:79], v8 offset:96
	ds_read_b32 v80, v7
	ds_read_b32 v81, v7 offset:256
	ds_read_b32 v82, v7 offset:512
	ds_read_b32 v83, v7 offset:768
	ds_read_b32 v84, v7 offset:1024
	ds_read_b32 v85, v7 offset:1280
	ds_read_b32 v86, v7 offset:1536
	ds_read_b32 v87, v7 offset:1792
	ds_read_b32 v88, v7 offset:2048
	ds_read_b32 v89, v7 offset:2304
	ds_read_b32 v90, v7 offset:2560
	ds_read_b32 v91, v7 offset:2816
	ds_read_b32 v92, v7 offset:3072
	ds_read_b32 v93, v7 offset:3328
	ds_read_b32 v94, v7 offset:3584
	ds_read_b32 v95, v7 offset:3840
	s_or_b32 s6, s8, 0x7f
	v_lshlrev_b32_e32 v0, 1, v200
	v_lshl_add_u64 v[2:3], s[70:71], 0, v[0:1]
	v_sub_u32_e32 v0, s6, v6
	v_add_u32_e32 v4, s8, v6
	v_cndmask_b32_e64 v4, v0, v4, s[4:5]
	v_ashrrev_i32_e32 v5, 31, v4
	v_lshlrev_b64 v[4:5], 9, v[4:5]
	v_lshl_add_u64 v[4:5], v[2:3], 0, v[4:5]
	s_and_b64 vcc, exec, s[4:5]
	s_cbranch_vccz .Lssd_y2_bwd
	v_add_co_u32_e32 v96, vcc, 0x1000, v4
	v_addc_co_u32_e32 v97, vcc, 0, v5, vcc
	v_add_co_u32_e32 v98, vcc, 0x2000, v4
	v_addc_co_u32_e32 v99, vcc, 0, v5, vcc
	v_add_co_u32_e32 v8, vcc, 0x3000, v4
	v_addc_co_u32_e32 v9, vcc, 0, v5, vcc
	s_waitcnt lgkmcnt(0)
	v_mul_f32_e32 v64, 0x3fb8aa3b, v64
	v_mul_f32_e32 v65, 0x3fb8aa3b, v65
	v_mul_f32_e32 v66, 0x3fb8aa3b, v66
	v_mul_f32_e32 v67, 0x3fb8aa3b, v67
	v_exp_f32_e32 v64, v64
	v_exp_f32_e32 v65, v65
	v_exp_f32_e32 v66, v66
	v_exp_f32_e32 v67, v67
	v_add_f32_e32 v80, v48, v80
	v_add_f32_e32 v81, v49, v81
	v_add_f32_e32 v82, v50, v82
	v_add_f32_e32 v83, v51, v83
	v_fmac_f32_e32 v80, v32, v64
	v_fmac_f32_e32 v81, v33, v65
	v_fmac_f32_e32 v82, v34, v66
	v_fmac_f32_e32 v83, v35, v67
	v_cvt_pk_bf16_f32 v80, v80, v1
	v_cvt_pk_bf16_f32 v81, v81, v1
	v_cvt_pk_bf16_f32 v82, v82, v1
	v_cvt_pk_bf16_f32 v83, v83, v1
	global_store_short v[4:5], v80, off
	global_store_short v[4:5], v81, off offset:512
	global_store_short v[4:5], v82, off offset:1024
	global_store_short v[4:5], v83, off offset:1536
	v_mul_f32_e32 v68, 0x3fb8aa3b, v68
	v_mul_f32_e32 v69, 0x3fb8aa3b, v69
	v_mul_f32_e32 v70, 0x3fb8aa3b, v70
	v_mul_f32_e32 v71, 0x3fb8aa3b, v71
	v_exp_f32_e32 v68, v68
	v_exp_f32_e32 v69, v69
	v_exp_f32_e32 v70, v70
	v_exp_f32_e32 v71, v71
	v_add_f32_e32 v84, v52, v84
	v_add_f32_e32 v85, v53, v85
	v_add_f32_e32 v86, v54, v86
	v_add_f32_e32 v87, v55, v87
	v_fmac_f32_e32 v84, v36, v68
	v_fmac_f32_e32 v85, v37, v69
	v_fmac_f32_e32 v86, v38, v70
	v_fmac_f32_e32 v87, v39, v71
	v_cvt_pk_bf16_f32 v84, v84, v1
	v_cvt_pk_bf16_f32 v85, v85, v1
	v_cvt_pk_bf16_f32 v86, v86, v1
	v_cvt_pk_bf16_f32 v87, v87, v1
	global_store_short v[96:97], v84, off
	global_store_short v[96:97], v85, off offset:512
	global_store_short v[96:97], v86, off offset:1024
	global_store_short v[96:97], v87, off offset:1536
	v_mul_f32_e32 v72, 0x3fb8aa3b, v72
	v_mul_f32_e32 v73, 0x3fb8aa3b, v73
	v_mul_f32_e32 v74, 0x3fb8aa3b, v74
	v_mul_f32_e32 v75, 0x3fb8aa3b, v75
	v_exp_f32_e32 v72, v72
	v_exp_f32_e32 v73, v73
	v_exp_f32_e32 v74, v74
	v_exp_f32_e32 v75, v75
	v_add_f32_e32 v88, v56, v88
	v_add_f32_e32 v89, v57, v89
	v_add_f32_e32 v90, v58, v90
	v_add_f32_e32 v91, v59, v91
	v_fmac_f32_e32 v88, v40, v72
	v_fmac_f32_e32 v89, v41, v73
	v_fmac_f32_e32 v90, v42, v74
	v_fmac_f32_e32 v91, v43, v75
	v_cvt_pk_bf16_f32 v88, v88, v1
	v_cvt_pk_bf16_f32 v89, v89, v1
	v_cvt_pk_bf16_f32 v90, v90, v1
	v_cvt_pk_bf16_f32 v91, v91, v1
	global_store_short v[98:99], v88, off
	global_store_short v[98:99], v89, off offset:512
	global_store_short v[98:99], v90, off offset:1024
	global_store_short v[98:99], v91, off offset:1536
	v_mul_f32_e32 v76, 0x3fb8aa3b, v76
	v_mul_f32_e32 v77, 0x3fb8aa3b, v77
	v_mul_f32_e32 v78, 0x3fb8aa3b, v78
	v_mul_f32_e32 v79, 0x3fb8aa3b, v79
	v_exp_f32_e32 v76, v76
	v_exp_f32_e32 v77, v77
	v_exp_f32_e32 v78, v78
	v_exp_f32_e32 v79, v79
	v_add_f32_e32 v92, v60, v92
	v_add_f32_e32 v93, v61, v93
	v_add_f32_e32 v94, v62, v94
	v_add_f32_e32 v95, v63, v95
	v_fmac_f32_e32 v92, v44, v76
	v_fmac_f32_e32 v93, v45, v77
	v_fmac_f32_e32 v94, v46, v78
	v_fmac_f32_e32 v95, v47, v79
	v_cvt_pk_bf16_f32 v92, v92, v1
	v_cvt_pk_bf16_f32 v93, v93, v1
	v_cvt_pk_bf16_f32 v94, v94, v1
	v_cvt_pk_bf16_f32 v95, v95, v1
	global_store_short v[8:9], v92, off
	global_store_short v[8:9], v93, off offset:512
	global_store_short v[8:9], v94, off offset:1024
	global_store_short v[8:9], v95, off offset:1536
	s_branch .Lssd_y2_done
.Lssd_y2_bwd:
	v_add_co_u32_e32 v96, vcc, 0xfffff000, v4
	v_addc_co_u32_e32 v97, vcc, -1, v5, vcc
	v_add_co_u32_e32 v98, vcc, 0xffffe000, v4
	v_addc_co_u32_e32 v99, vcc, -1, v5, vcc
	v_add_co_u32_e32 v8, vcc, 0xffffd000, v4
	v_addc_co_u32_e32 v9, vcc, -1, v5, vcc
	s_waitcnt lgkmcnt(0)
	v_mul_f32_e32 v64, 0x3fb8aa3b, v64
	v_mul_f32_e32 v65, 0x3fb8aa3b, v65
	v_mul_f32_e32 v66, 0x3fb8aa3b, v66
	v_mul_f32_e32 v67, 0x3fb8aa3b, v67
	v_exp_f32_e32 v64, v64
	v_exp_f32_e32 v65, v65
	v_exp_f32_e32 v66, v66
	v_exp_f32_e32 v67, v67
	v_add_f32_e32 v80, v48, v80
	v_add_f32_e32 v81, v49, v81
	v_add_f32_e32 v82, v50, v82
	v_add_f32_e32 v83, v51, v83
	v_fmac_f32_e32 v80, v32, v64
	v_fmac_f32_e32 v81, v33, v65
	v_fmac_f32_e32 v82, v34, v66
	v_fmac_f32_e32 v83, v35, v67
	v_cvt_pk_bf16_f32 v80, v80, v1
	v_cvt_pk_bf16_f32 v81, v81, v1
	v_cvt_pk_bf16_f32 v82, v82, v1
	v_cvt_pk_bf16_f32 v83, v83, v1
	global_store_short v[4:5], v80, off
	global_store_short v[4:5], v81, off offset:-512
	global_store_short v[4:5], v82, off offset:-1024
	global_store_short v[4:5], v83, off offset:-1536
	v_mul_f32_e32 v68, 0x3fb8aa3b, v68
	v_mul_f32_e32 v69, 0x3fb8aa3b, v69
	v_mul_f32_e32 v70, 0x3fb8aa3b, v70
	v_mul_f32_e32 v71, 0x3fb8aa3b, v71
	v_exp_f32_e32 v68, v68
	v_exp_f32_e32 v69, v69
	v_exp_f32_e32 v70, v70
	v_exp_f32_e32 v71, v71
	v_add_f32_e32 v84, v52, v84
	v_add_f32_e32 v85, v53, v85
	v_add_f32_e32 v86, v54, v86
	v_add_f32_e32 v87, v55, v87
	v_fmac_f32_e32 v84, v36, v68
	v_fmac_f32_e32 v85, v37, v69
	v_fmac_f32_e32 v86, v38, v70
	v_fmac_f32_e32 v87, v39, v71
	v_cvt_pk_bf16_f32 v84, v84, v1
	v_cvt_pk_bf16_f32 v85, v85, v1
	v_cvt_pk_bf16_f32 v86, v86, v1
	v_cvt_pk_bf16_f32 v87, v87, v1
	global_store_short v[96:97], v84, off
	global_store_short v[96:97], v85, off offset:-512
	global_store_short v[96:97], v86, off offset:-1024
	global_store_short v[96:97], v87, off offset:-1536
	v_mul_f32_e32 v72, 0x3fb8aa3b, v72
	v_mul_f32_e32 v73, 0x3fb8aa3b, v73
	v_mul_f32_e32 v74, 0x3fb8aa3b, v74
	v_mul_f32_e32 v75, 0x3fb8aa3b, v75
	v_exp_f32_e32 v72, v72
	v_exp_f32_e32 v73, v73
	v_exp_f32_e32 v74, v74
	v_exp_f32_e32 v75, v75
	v_add_f32_e32 v88, v56, v88
	v_add_f32_e32 v89, v57, v89
	v_add_f32_e32 v90, v58, v90
	v_add_f32_e32 v91, v59, v91
	v_fmac_f32_e32 v88, v40, v72
	v_fmac_f32_e32 v89, v41, v73
	v_fmac_f32_e32 v90, v42, v74
	v_fmac_f32_e32 v91, v43, v75
	v_cvt_pk_bf16_f32 v88, v88, v1
	v_cvt_pk_bf16_f32 v89, v89, v1
	v_cvt_pk_bf16_f32 v90, v90, v1
	v_cvt_pk_bf16_f32 v91, v91, v1
	global_store_short v[98:99], v88, off
	global_store_short v[98:99], v89, off offset:-512
	global_store_short v[98:99], v90, off offset:-1024
	global_store_short v[98:99], v91, off offset:-1536
	v_mul_f32_e32 v76, 0x3fb8aa3b, v76
	v_mul_f32_e32 v77, 0x3fb8aa3b, v77
	v_mul_f32_e32 v78, 0x3fb8aa3b, v78
	v_mul_f32_e32 v79, 0x3fb8aa3b, v79
	v_exp_f32_e32 v76, v76
	v_exp_f32_e32 v77, v77
	v_exp_f32_e32 v78, v78
	v_exp_f32_e32 v79, v79
	v_add_f32_e32 v92, v60, v92
	v_add_f32_e32 v93, v61, v93
	v_add_f32_e32 v94, v62, v94
	v_add_f32_e32 v95, v63, v95
	v_fmac_f32_e32 v92, v44, v76
	v_fmac_f32_e32 v93, v45, v77
	v_fmac_f32_e32 v94, v46, v78
	v_fmac_f32_e32 v95, v47, v79
	v_cvt_pk_bf16_f32 v92, v92, v1
	v_cvt_pk_bf16_f32 v93, v93, v1
	v_cvt_pk_bf16_f32 v94, v94, v1
	v_cvt_pk_bf16_f32 v95, v95, v1
	global_store_short v[8:9], v92, off
	global_store_short v[8:9], v93, off offset:-512
	global_store_short v[8:9], v94, off offset:-1024
	global_store_short v[8:9], v95, off offset:-1536
.Lssd_y2_done:
.LBB0_828:
	s_cbranch_execz .LBB0_831
